# hand-written WKV7 scan phase: time-major producer lanes, reg-fed MFMA products, consumer alone on its SIMD
# speedup vs baseline: 1.0185x; 1.0185x over previous
; #define LAS __attribute__((address_space(3)))
; __device__ __forceinline__ int otid() { int t = threadIdx.x; asm volatile("" : "+v"(t)); return t; }
; __device__ __forceinline__ int obid() { int b = blockIdx.x; asm volatile("" : "+s"(b)); return b; }
; __device__ __forceinline__ void phase_scan2(const Params& p, int l, LAS unsigned char* lds) {
;     ...
;     const int tid = otid(), wid = tid >> 6, lane = tid & 63, fr = lane & 15, fq = lane >> 4;
;     constexpr int NCH = SEQ / 16, NRD = (NCH + SC_NP - 1) / SC_NP;
;     for (int job = obid(); job < 256; job += gridDim.x) {
;         const int bh = job >> 2, rg = job & 3, b = bh >> 3, h = bh & 7;
;         const size_t tok0 = (size_t)b * SEQ;
;         const int pw = wid - 3, j = lane;
;         const float kkc = k_k[h * 64 + j], kac = k_a[h * 64 + j], rkc = r_k[h * 64 + j];
;         unsigned short kraw[16], araw[16], rraw[16]; _Float16 eraw[16]; unsigned short vraw[4];
; #pragma unroll
;         for (int t = 0; t < 16; ++t) { kraw[t] = 0; araw[t] = 0; rraw[t] = 0; eraw[t] = (_Float16)0; }
; #pragma unroll
;         for (int q = 0; q < 4; ++q) vraw[q] = 0;
;         auto pload = [&](int c) {
;             const size_t base = (tok0 + (size_t)c * 16) * 512 + h * 64;
; #pragma unroll
;             for (int t = 0; t < 16; ++t) { const size_t off = base + (size_t)t * 512 + j; kraw[t] = Kb[off]; araw[t] = Ab[off]; rraw[t] = Rb[off]; eraw[t] = EW[off]; }
; #pragma unroll
;             for (int q = 0; q < 4; ++q) vraw[q] = Vb[base + (size_t)(4 * fq + q) * 512 + rg * 16 + fr];
;         };
;     ...
;         LAS unsigned char* scr = lds + SC_RING + (pw < 0 ? 0 : pw) * SC_SCR;
;         if (wid >= 3) { pload(pw); pbuild(pw, lds + pw * SC_SLOT, scr, SC_NP + pw); }
.Lsc_entry:
	s_mov_b32 s13, s5
	v_and_b32_e32 v0, 63, v183
	v_and_b32_e32 v1, 15, v183
	v_bfe_u32 v2, v183, 4, 2
	v_lshrrev_b32_e32 v4, 6, v183
	s_nop 0
	v_readfirstlane_b32 s25, v4
	v_lshlrev_b32_e32 v6, 5, v1
	v_lshl_add_u32 v6, v2, 3, v6
	v_lshlrev_b32_e32 v7, 1, v1
	v_lshl_add_u32 v7, v2, 7, v7
	s_add_u32 s26, s74, 0xc000000
	s_addc_u32 s27, s75, 0
	s_add_u32 s36, s74, 0x13000000
	s_addc_u32 s37, s75, 0
	s_add_u32 s38, s74, 0xa000000
	s_addc_u32 s39, s75, 0
	s_add_u32 s46, s74, 0x11000000
	s_addc_u32 s47, s75, 0
.Lsc_job:
	s_lshr_b32 s0, s13, 2
	s_and_b32 s53, s13, 3
	s_lshr_b32 s54, s0, 3
	s_and_b32 s52, s0, 7
	s_cmp_eq_u32 s25, 0
	s_cbranch_scc1 .Lsc_consumer
	s_cmp_eq_u32 s25, 4
	s_cbranch_scc1 .Lsc_idle
	s_cmp_eq_u32 s25, 7
	s_cbranch_scc1 .Lsc_idle
.Lsc_producer:
	s_sub_u32 s55, s25, 1
	s_cmp_gt_u32 s25, 4
	s_cselect_b32 s0, 1, 0
	s_sub_u32 s55, s55, s0
	v_mov_b32_e32 v22, 1.0
	v_mov_b32_e32 v23, 1.0
	v_mov_b32_e32 v24, 0xbfb8aa3b
	v_mov_b32_e32 v25, 0xbfb8aa3b
	v_mov_b32_e32 v28, 0x3f803f80
	v_mov_b32_e32 v29, 0x3f803f80
	v_mov_b32_e32 v30, 0x3f803f80
	v_mov_b32_e32 v31, 0x3f803f80
	v_cmp_eq_u32_e32 vcc, 0, v1
	s_nop 1
	v_cndmask_b32_e64 v26, 0, 1.0, vcc
	v_lshl_add_u32 v4, v2, 2, 0
	v_cmp_eq_u32_e32 vcc, v4, v1
	s_nop 1
	v_cndmask_b32_e64 v27, 0, 1.0, vcc
	v_cmp_gt_u32_e32 vcc, v4, v1
	s_nop 1
	v_cndmask_b32_e64 v35, 0, 1.0, vcc
	v_cmp_ge_u32_e32 vcc, v4, v1
	s_nop 1
	v_cndmask_b32_e64 v39, 0, 1.0, vcc
	v_lshl_add_u32 v4, v2, 2, 1
	v_cmp_eq_u32_e32 vcc, v4, v1
	s_nop 1
	v_cndmask_b32_e64 v32, 0, 1.0, vcc
	v_cmp_gt_u32_e32 vcc, v4, v1
	s_nop 1
	v_cndmask_b32_e64 v36, 0, 1.0, vcc
	v_cmp_ge_u32_e32 vcc, v4, v1
	s_nop 1
	v_cndmask_b32_e64 v40, 0, 1.0, vcc
	v_lshl_add_u32 v4, v2, 2, 2
	v_cmp_eq_u32_e32 vcc, v4, v1
	s_nop 1
	v_cndmask_b32_e64 v33, 0, 1.0, vcc
	v_cmp_gt_u32_e32 vcc, v4, v1
	s_nop 1
	v_cndmask_b32_e64 v37, 0, 1.0, vcc
	v_cmp_ge_u32_e32 vcc, v4, v1
	s_nop 1
	v_cndmask_b32_e64 v41, 0, 1.0, vcc
	v_lshl_add_u32 v4, v2, 2, 3
	v_cmp_eq_u32_e32 vcc, v4, v1
	s_nop 1
	v_cndmask_b32_e64 v34, 0, 1.0, vcc
	v_cmp_gt_u32_e32 vcc, v4, v1
	s_nop 1
	v_cndmask_b32_e64 v38, 0, 1.0, vcc
	v_cmp_ge_u32_e32 vcc, v4, v1
	s_nop 1
	v_cndmask_b32_e64 v42, 0, 1.0, vcc
	s_lshl_b32 s0, s52, 8
	v_lshl_add_u32 v4, v0, 2, s0
	v_readlane_b32 s14, v243, 51
	v_readlane_b32 s15, v243, 52
	s_nop 0
	s_lshl_b64 s[14:15], s[14:15], 2
	v_readlane_b32 s0, v252, 36
	v_readlane_b32 s1, v252, 37
	s_add_u32 s0, s0, s14
	s_addc_u32 s1, s1, s15
	global_load_dword v76, v4, s[0:1]
	v_readlane_b32 s0, v252, 38
	v_readlane_b32 s1, v252, 39
	s_add_u32 s0, s0, s14
	s_addc_u32 s1, s1, s15
	global_load_dword v80, v4, s[0:1]
	v_readlane_b32 s0, v252, 40
	v_readlane_b32 s1, v252, 41
	s_add_u32 s0, s0, s14
	s_addc_u32 s1, s1, s15
	global_load_dword v176, v4, s[0:1]
	s_mul_i32 s0, s54, 4096
	s_lshl_b32 s1, s55, 4
	s_add_u32 s1, s1, s0
	v_add_u32_e32 v8, s1, v1
	v_lshlrev_b32_e32 v8, 10, v8
	s_lshl_b32 s14, s52, 7
	v_lshl_add_u32 v4, v2, 5, s14
	v_add_u32_e32 v8, v8, v4
	v_lshl_add_u32 v9, v2, 2, s1
	v_lshlrev_b32_e32 v9, 10, v9
	s_lshl_b32 s15, s53, 5
	s_add_u32 s14, s14, s15
	v_lshl_add_u32 v4, v1, 1, s14
	v_add_u32_e32 v9, v9, v4
	v_lshlrev_b32_e32 v10, 5, v1
	v_lshrrev_b32_e32 v4, 1, v2
	v_lshlrev_b32_e32 v11, 10, v4
	v_lshl_add_u32 v11, v1, 6, v11
	v_and_b32_e32 v4, 1, v2
	v_lshl_add_u32 v11, v4, 3, v11
	v_mul_u32_u24_e32 v13, 640, v2
	v_lshl_add_u32 v13, v1, 1, v13
	v_add_u32_e32 v13, 4096, v13
	v_lshlrev_b32_e32 v16, 6, v2
	v_add_u32_e32 v16, 11776, v16
	s_mul_i32 s0, s55, 6144
	s_add_u32 s0, s0, 122880
	v_add_u32_e32 v14, s0, v7
	v_add_u32_e32 v15, s0, v6
	v_lshl_add_u32 v4, v0, 2, s0
	s_waitcnt vmcnt(0)
	ds_write_b32 v4, v76 offset:5120
	ds_write_b32 v4, v80 offset:5376
	ds_write_b32 v4, v176 offset:5632
	v_lshl_add_u32 v43, v2, 6, s0
	s_mul_i32 s57, s55, 12288
	s_mov_b32 s56, 0
	s_lshl_b32 s0, s1, 5
	s_lshl_b32 s14, s52, 2
	s_add_u32 s0, s0, s14
	s_add_u32 s0, s0, 0x9000000
	s_add_u32 s50, s74, s0
	s_addc_u32 s51, s75, 0
	s_mov_b32 s58, s55
	s_mov_b32 s42, 0
	global_load_dwordx4 v[44:47], v8, s[26:27]
	global_load_dwordx4 v[48:51], v8, s[26:27] offset:16
	global_load_dwordx4 v[52:55], v8, s[36:37]
	global_load_dwordx4 v[56:59], v8, s[36:37] offset:16
	global_load_dwordx4 v[60:63], v8, s[38:39]
	global_load_dwordx4 v[64:67], v8, s[38:39] offset:16
	global_load_dwordx4 v[68:71], v8, s[46:47]
	global_load_dwordx4 v[72:75], v8, s[46:47] offset:16
	global_load_ushort v84, v9, s[60:61] offset:0
	global_load_ushort v85, v9, s[60:61] offset:1024
	global_load_ushort v86, v9, s[60:61] offset:2048
	global_load_ushort v87, v9, s[60:61] offset:3072
	v_add_u32_e32 v8, 0x14000, v8
	v_add_u32_e32 v9, 0x14000, v9
	s_nop 1
; #define LAS __attribute__((address_space(3)))
; __device__ __forceinline__ float bf2f(bf16_t b) { return __uint_as_float(((unsigned)b) << 16); }
; __device__ __forceinline__ bf16_t bf1(float x) { return (bf16_t)(pk_bf16(x, 0.f) & 0xffffu); }
; __device__ __forceinline__ void phase_scan2(const Params& p, int l, LAS unsigned char* lds) {
;     ...
;         auto pbuild = [&](int c, LAS unsigned char* sl, LAS unsigned char* sc, int cnext) {
;             float W = 1.f;
;             const int m = j >> 5, tp = (j >> 4) & 1, jw = j & 15, pidx = (jw >> 2) * 8 + tp * 4 + (jw & 3);
; #pragma unroll
;             for (int t = 0; t < 16; ++t) {
;                 const float k = bf2f(kraw[t]), a = bf2f(araw[t]), r = bf2f(rraw[t]);
;                 const float q = k * kkc, kp1 = k * (1.f + (a - 1.f) * kac);
;                 *(LAS bf16_t*)(sc + 0 + (t * 64 + j) * 2) = bf1(q * q);
;                 *(LAS bf16_t*)(sc + 2048 + (t * 64 + j) * 2) = bf1(r * kp1 * rkc);
;             }
;     ...
;             if (cnext >= 0) pload(cnext);
.Lsc_p_loop:
	s_cmp_ge_u32 s58, 256
	s_cbranch_scc1 .Lsc_p_skip
	s_add_u32 s0, s57, s56
	v_add_u32_e32 v17, s0, v11
	v_add_u32_e32 v18, s0, v13
	v_add_u32_e32 v19, s0, v6
	v_add_u32_e32 v20, s0, v7
	v_add_u32_e32 v21, s0, v16
	s_waitcnt vmcnt(0)
	v_and_b32_e32 v89, 0xffff0000, v44
	v_lshlrev_b32_e32 v88, 16, v44
	v_and_b32_e32 v105, 0xffff0000, v52
	v_lshlrev_b32_e32 v104, 16, v52
	v_and_b32_e32 v121, 0xffff0000, v60
	v_lshlrev_b32_e32 v120, 16, v60
	v_cvt_f32_f16_sdwa v153, v68 dst_sel:DWORD dst_unused:UNUSED_PAD src0_sel:WORD_1
	v_cvt_f32_f16_e32 v152, v68
	v_and_b32_e32 v91, 0xffff0000, v45
	v_lshlrev_b32_e32 v90, 16, v45
	v_and_b32_e32 v107, 0xffff0000, v53
	v_lshlrev_b32_e32 v106, 16, v53
	v_and_b32_e32 v123, 0xffff0000, v61
	v_lshlrev_b32_e32 v122, 16, v61
	v_cvt_f32_f16_sdwa v155, v69 dst_sel:DWORD dst_unused:UNUSED_PAD src0_sel:WORD_1
	v_cvt_f32_f16_e32 v154, v69
	v_and_b32_e32 v93, 0xffff0000, v46
	v_lshlrev_b32_e32 v92, 16, v46
	v_and_b32_e32 v109, 0xffff0000, v54
	v_lshlrev_b32_e32 v108, 16, v54
	v_and_b32_e32 v125, 0xffff0000, v62
	v_lshlrev_b32_e32 v124, 16, v62
	v_cvt_f32_f16_sdwa v157, v70 dst_sel:DWORD dst_unused:UNUSED_PAD src0_sel:WORD_1
	v_cvt_f32_f16_e32 v156, v70
	v_and_b32_e32 v95, 0xffff0000, v47
	v_lshlrev_b32_e32 v94, 16, v47
	v_and_b32_e32 v111, 0xffff0000, v55
	v_lshlrev_b32_e32 v110, 16, v55
	v_and_b32_e32 v127, 0xffff0000, v63
	v_lshlrev_b32_e32 v126, 16, v63
	v_cvt_f32_f16_sdwa v159, v71 dst_sel:DWORD dst_unused:UNUSED_PAD src0_sel:WORD_1
	v_cvt_f32_f16_e32 v158, v71
	v_and_b32_e32 v97, 0xffff0000, v48
	v_lshlrev_b32_e32 v96, 16, v48
	v_and_b32_e32 v113, 0xffff0000, v56
	v_lshlrev_b32_e32 v112, 16, v56
	v_and_b32_e32 v129, 0xffff0000, v64
	v_lshlrev_b32_e32 v128, 16, v64
	v_cvt_f32_f16_sdwa v161, v72 dst_sel:DWORD dst_unused:UNUSED_PAD src0_sel:WORD_1
	v_cvt_f32_f16_e32 v160, v72
	v_and_b32_e32 v99, 0xffff0000, v49
	v_lshlrev_b32_e32 v98, 16, v49
	v_and_b32_e32 v115, 0xffff0000, v57
	v_lshlrev_b32_e32 v114, 16, v57
	v_and_b32_e32 v131, 0xffff0000, v65
	v_lshlrev_b32_e32 v130, 16, v65
	v_cvt_f32_f16_sdwa v163, v73 dst_sel:DWORD dst_unused:UNUSED_PAD src0_sel:WORD_1
	v_cvt_f32_f16_e32 v162, v73
	v_and_b32_e32 v101, 0xffff0000, v50
	v_lshlrev_b32_e32 v100, 16, v50
	v_and_b32_e32 v117, 0xffff0000, v58
	v_lshlrev_b32_e32 v116, 16, v58
	v_and_b32_e32 v133, 0xffff0000, v66
	v_lshlrev_b32_e32 v132, 16, v66
	v_cvt_f32_f16_sdwa v165, v74 dst_sel:DWORD dst_unused:UNUSED_PAD src0_sel:WORD_1
	v_cvt_f32_f16_e32 v164, v74
	v_and_b32_e32 v103, 0xffff0000, v51
	v_lshlrev_b32_e32 v102, 16, v51
	v_and_b32_e32 v119, 0xffff0000, v59
	v_lshlrev_b32_e32 v118, 16, v59
	v_and_b32_e32 v135, 0xffff0000, v67
	v_lshlrev_b32_e32 v134, 16, v67
	v_cvt_f32_f16_sdwa v167, v75 dst_sel:DWORD dst_unused:UNUSED_PAD src0_sel:WORD_1
	v_cvt_f32_f16_e32 v166, v75
	v_lshl_or_b32 v76, v85, 16, v84
	v_lshl_or_b32 v77, v87, 16, v86
	ds_write_b64 v19, v[76:77] offset:11264
	s_add_u32 s0, s58, 5
	s_cmp_ge_u32 s0, 256
	s_cbranch_scc1 .Lsc_p_nopf
	global_load_dwordx4 v[44:47], v8, s[26:27]
	global_load_dwordx4 v[48:51], v8, s[26:27] offset:16
	global_load_dwordx4 v[52:55], v8, s[36:37]
	global_load_dwordx4 v[56:59], v8, s[36:37] offset:16
	global_load_dwordx4 v[60:63], v8, s[38:39]
	global_load_dwordx4 v[64:67], v8, s[38:39] offset:16
	global_load_dwordx4 v[68:71], v8, s[46:47]
	global_load_dwordx4 v[72:75], v8, s[46:47] offset:16
	global_load_ushort v84, v9, s[60:61] offset:0
	global_load_ushort v85, v9, s[60:61] offset:1024
	global_load_ushort v86, v9, s[60:61] offset:2048
	global_load_ushort v87, v9, s[60:61] offset:3072
	v_add_u32_e32 v8, 0x14000, v8
	v_add_u32_e32 v9, 0x14000, v9
	s_nop 1
.Lsc_p_nopf:
	ds_read_b128 v[220:223], v43 offset:5376
	ds_read_b128 v[224:227], v43 offset:5392
	ds_read_b128 v[228:231], v43 offset:5120
	ds_read_b128 v[232:235], v43 offset:5136
	ds_read_b128 v[236:239], v43 offset:5632
	ds_read_b128 v[244:247], v43 offset:5648
	s_waitcnt lgkmcnt(4)
	v_add_f32_e32 v76, -1.0, v104
	v_add_f32_e32 v77, -1.0, v105
	v_pk_fma_f32 v[76:77], v[220:221], v[76:77], v[22:23]
	v_pk_mul_f32 v[136:137], v[76:77], v[88:89]
	s_waitcnt lgkmcnt(2)
	v_pk_mul_f32 v[88:89], v[228:229], v[88:89]
	v_pk_mul_f32 v[80:81], v[88:89], v[88:89]
	v_pk_mul_f32 v[176:177], v[136:137], v[120:121]
	v_cvt_pk_bf16_f32 v196, v80, v81
	s_waitcnt lgkmcnt(0)
	v_pk_mul_f32 v[176:177], v[236:237], v[176:177]
	v_cvt_pk_bf16_f32 v204, v176, v177
	v_add_f32_e32 v76, -1.0, v106
	v_add_f32_e32 v77, -1.0, v107
	v_pk_fma_f32 v[76:77], v[222:223], v[76:77], v[22:23]
	v_pk_mul_f32 v[138:139], v[76:77], v[90:91]
	v_pk_mul_f32 v[90:91], v[230:231], v[90:91]
	v_pk_mul_f32 v[80:81], v[90:91], v[90:91]
	v_pk_mul_f32 v[176:177], v[138:139], v[122:123]
	v_cvt_pk_bf16_f32 v197, v80, v81
	v_pk_mul_f32 v[176:177], v[238:239], v[176:177]
	v_cvt_pk_bf16_f32 v205, v176, v177
	s_waitcnt lgkmcnt(3)
	v_add_f32_e32 v76, -1.0, v108
	v_add_f32_e32 v77, -1.0, v109
	v_pk_fma_f32 v[76:77], v[224:225], v[76:77], v[22:23]
	v_pk_mul_f32 v[140:141], v[76:77], v[92:93]
	s_waitcnt lgkmcnt(1)
	v_pk_mul_f32 v[92:93], v[232:233], v[92:93]
	v_pk_mul_f32 v[80:81], v[92:93], v[92:93]
	v_pk_mul_f32 v[176:177], v[140:141], v[124:125]
	v_cvt_pk_bf16_f32 v198, v80, v81
	s_waitcnt lgkmcnt(0)
	v_pk_mul_f32 v[176:177], v[244:245], v[176:177]
	v_cvt_pk_bf16_f32 v206, v176, v177
	v_add_f32_e32 v76, -1.0, v110
	v_add_f32_e32 v77, -1.0, v111
	v_pk_fma_f32 v[76:77], v[226:227], v[76:77], v[22:23]
	v_pk_mul_f32 v[142:143], v[76:77], v[94:95]
	v_pk_mul_f32 v[94:95], v[234:235], v[94:95]
	v_pk_mul_f32 v[80:81], v[94:95], v[94:95]
	v_pk_mul_f32 v[176:177], v[142:143], v[126:127]
	v_cvt_pk_bf16_f32 v199, v80, v81
	v_pk_mul_f32 v[176:177], v[246:247], v[176:177]
	v_cvt_pk_bf16_f32 v207, v176, v177
	ds_read_b128 v[220:223], v43 offset:5408
	ds_read_b128 v[224:227], v43 offset:5424
	ds_read_b128 v[228:231], v43 offset:5152
	ds_read_b128 v[232:235], v43 offset:5168
	ds_read_b128 v[236:239], v43 offset:5664
	ds_read_b128 v[244:247], v43 offset:5680
	s_waitcnt lgkmcnt(4)
; #define LAS __attribute__((address_space(3)))
; __device__ __forceinline__ float bf2f(bf16_t b) { return __uint_as_float(((unsigned)b) << 16); }
; __device__ __forceinline__ void phase_scan2(const Params& p, int l, LAS unsigned char* lds) {
;     ...
;             { const bf16x8 ones = __builtin_bit_cast(bf16x8, (u32x4){0x3F803F80u, 0x3F803F80u, 0x3F803F80u, 0x3F803F80u});
;               f32x4 sq = (f32x4){0.f, 0.f, 0.f, 0.f}, sb = sq;
; #pragma unroll
;               for (int kk2 = 0; kk2 < 2; ++kk2) {
;                   const bf16x8 fa = *(LAS const bf16x8*)(sc + 0 + (fr * 64 + kk2 * 32 + fq * 8) * 2), fu = *(LAS const bf16x8*)(sc + 2048 + (fr * 64 + kk2 * 32 + fq * 8) * 2);
;                   sq = __builtin_amdgcn_mfma_f32_16x16x32_bf16(fa, ones, sq, 0, 0, 0); sb = __builtin_amdgcn_mfma_f32_16x16x32_bf16(fu, ones, sb, 0, 0, 0);
;               }
;               if (fr == 0) { *(LAS f32x4*)(sl + SC_X + fq * 16) = sq; *(LAS f32x4*)(sl + SC_X + 64 + fq * 16) = sb; }
;               asm volatile("s_waitcnt lgkmcnt(0)" ::: "memory");
;               if (rg == 0 && lane < 16) CB[(tok0 + (size_t)c * 16 + lane) * 8 + h] = *(LAS const float*)(sl + SC_X + 64 + lane * 4);
;               asm volatile("s_waitcnt lgkmcnt(0)" ::: "memory");
;             }
; #pragma unroll
;             for (int t = 0; t < 16; ++t) {
;                 const float k = bf2f(kraw[t]), a = bf2f(araw[t]), r = bf2f(rraw[t]), ew = (float)eraw[t];
;                 const float kk = k * kkc * rsqrtf(fmaxf(*(LAS const float*)(sl + SC_X + t * 4), 1e-24f));
;                 const float kp = k * (1.f + (a - 1.f) * kac);
;                 const float at = -kk * W;
;                 W *= __expf(-ew);
;                 const float rt = r * W, iw = __builtin_amdgcn_rcpf(W);
	v_add_f32_e32 v76, -1.0, v112
	v_add_f32_e32 v77, -1.0, v113
	v_pk_fma_f32 v[76:77], v[220:221], v[76:77], v[22:23]
	v_pk_mul_f32 v[144:145], v[76:77], v[96:97]
	s_waitcnt lgkmcnt(2)
	v_pk_mul_f32 v[96:97], v[228:229], v[96:97]
	v_pk_mul_f32 v[80:81], v[96:97], v[96:97]
	v_pk_mul_f32 v[176:177], v[144:145], v[128:129]
	v_cvt_pk_bf16_f32 v200, v80, v81
	s_waitcnt lgkmcnt(0)
	v_pk_mul_f32 v[176:177], v[236:237], v[176:177]
	v_cvt_pk_bf16_f32 v208, v176, v177
	v_add_f32_e32 v76, -1.0, v114
	v_add_f32_e32 v77, -1.0, v115
	v_pk_fma_f32 v[76:77], v[222:223], v[76:77], v[22:23]
	v_pk_mul_f32 v[146:147], v[76:77], v[98:99]
	v_pk_mul_f32 v[98:99], v[230:231], v[98:99]
	v_pk_mul_f32 v[80:81], v[98:99], v[98:99]
	v_pk_mul_f32 v[176:177], v[146:147], v[130:131]
	v_cvt_pk_bf16_f32 v201, v80, v81
	v_pk_mul_f32 v[176:177], v[238:239], v[176:177]
	v_cvt_pk_bf16_f32 v209, v176, v177
	s_waitcnt lgkmcnt(3)
	v_add_f32_e32 v76, -1.0, v116
	v_add_f32_e32 v77, -1.0, v117
	v_pk_fma_f32 v[76:77], v[224:225], v[76:77], v[22:23]
	v_pk_mul_f32 v[148:149], v[76:77], v[100:101]
	s_waitcnt lgkmcnt(1)
	v_pk_mul_f32 v[100:101], v[232:233], v[100:101]
	v_pk_mul_f32 v[80:81], v[100:101], v[100:101]
	v_pk_mul_f32 v[176:177], v[148:149], v[132:133]
	v_cvt_pk_bf16_f32 v202, v80, v81
	s_waitcnt lgkmcnt(0)
	v_pk_mul_f32 v[176:177], v[244:245], v[176:177]
	v_cvt_pk_bf16_f32 v210, v176, v177
	v_add_f32_e32 v76, -1.0, v118
	v_add_f32_e32 v77, -1.0, v119
	v_pk_fma_f32 v[76:77], v[226:227], v[76:77], v[22:23]
	v_pk_mul_f32 v[150:151], v[76:77], v[102:103]
	v_pk_mul_f32 v[102:103], v[234:235], v[102:103]
	v_pk_mul_f32 v[80:81], v[102:103], v[102:103]
	v_pk_mul_f32 v[176:177], v[150:151], v[134:135]
	v_cvt_pk_bf16_f32 v203, v80, v81
	v_pk_mul_f32 v[176:177], v[246:247], v[176:177]
	v_cvt_pk_bf16_f32 v211, v176, v177
	v_mfma_f32_16x16x32_bf16 v[168:171], v[28:31], v[196:199], 0
	v_mfma_f32_16x16x32_bf16 v[172:175], v[28:31], v[204:207], 0
	v_mfma_f32_16x16x32_bf16 v[168:171], v[28:31], v[200:203], v[168:171]
	v_mfma_f32_16x16x32_bf16 v[172:175], v[28:31], v[208:211], v[172:175]
	v_pk_mul_f32 v[152:153], v[152:153], v[24:25]
	v_pk_mul_f32 v[154:155], v[154:155], v[24:25]
	v_pk_mul_f32 v[156:157], v[156:157], v[24:25]
	v_pk_mul_f32 v[158:159], v[158:159], v[24:25]
	v_pk_mul_f32 v[160:161], v[160:161], v[24:25]
	v_pk_mul_f32 v[162:163], v[162:163], v[24:25]
	v_pk_mul_f32 v[164:165], v[164:165], v[24:25]
	v_pk_mul_f32 v[166:167], v[166:167], v[24:25]
	v_add_f32_dpp v152, v152, v152 row_shr:1 row_mask:0xf bank_mask:0xf bound_ctrl:1
	v_add_f32_dpp v153, v153, v153 row_shr:1 row_mask:0xf bank_mask:0xf bound_ctrl:1
	v_add_f32_dpp v154, v154, v154 row_shr:1 row_mask:0xf bank_mask:0xf bound_ctrl:1
	v_add_f32_dpp v155, v155, v155 row_shr:1 row_mask:0xf bank_mask:0xf bound_ctrl:1
	v_add_f32_dpp v156, v156, v156 row_shr:1 row_mask:0xf bank_mask:0xf bound_ctrl:1
	v_add_f32_dpp v157, v157, v157 row_shr:1 row_mask:0xf bank_mask:0xf bound_ctrl:1
	v_add_f32_dpp v158, v158, v158 row_shr:1 row_mask:0xf bank_mask:0xf bound_ctrl:1
	v_add_f32_dpp v159, v159, v159 row_shr:1 row_mask:0xf bank_mask:0xf bound_ctrl:1
	v_add_f32_dpp v160, v160, v160 row_shr:1 row_mask:0xf bank_mask:0xf bound_ctrl:1
	v_add_f32_dpp v161, v161, v161 row_shr:1 row_mask:0xf bank_mask:0xf bound_ctrl:1
	v_add_f32_dpp v162, v162, v162 row_shr:1 row_mask:0xf bank_mask:0xf bound_ctrl:1
	v_add_f32_dpp v163, v163, v163 row_shr:1 row_mask:0xf bank_mask:0xf bound_ctrl:1
	v_add_f32_dpp v164, v164, v164 row_shr:1 row_mask:0xf bank_mask:0xf bound_ctrl:1
	v_add_f32_dpp v165, v165, v165 row_shr:1 row_mask:0xf bank_mask:0xf bound_ctrl:1
	v_add_f32_dpp v166, v166, v166 row_shr:1 row_mask:0xf bank_mask:0xf bound_ctrl:1
	v_add_f32_dpp v167, v167, v167 row_shr:1 row_mask:0xf bank_mask:0xf bound_ctrl:1
	v_add_f32_dpp v152, v152, v152 row_shr:2 row_mask:0xf bank_mask:0xf bound_ctrl:1
	v_add_f32_dpp v153, v153, v153 row_shr:2 row_mask:0xf bank_mask:0xf bound_ctrl:1
	v_add_f32_dpp v154, v154, v154 row_shr:2 row_mask:0xf bank_mask:0xf bound_ctrl:1
	v_add_f32_dpp v155, v155, v155 row_shr:2 row_mask:0xf bank_mask:0xf bound_ctrl:1
	v_add_f32_dpp v156, v156, v156 row_shr:2 row_mask:0xf bank_mask:0xf bound_ctrl:1
	v_add_f32_dpp v157, v157, v157 row_shr:2 row_mask:0xf bank_mask:0xf bound_ctrl:1
	v_add_f32_dpp v158, v158, v158 row_shr:2 row_mask:0xf bank_mask:0xf bound_ctrl:1
	v_add_f32_dpp v159, v159, v159 row_shr:2 row_mask:0xf bank_mask:0xf bound_ctrl:1
	v_add_f32_dpp v160, v160, v160 row_shr:2 row_mask:0xf bank_mask:0xf bound_ctrl:1
	v_add_f32_dpp v161, v161, v161 row_shr:2 row_mask:0xf bank_mask:0xf bound_ctrl:1
	v_add_f32_dpp v162, v162, v162 row_shr:2 row_mask:0xf bank_mask:0xf bound_ctrl:1
	v_add_f32_dpp v163, v163, v163 row_shr:2 row_mask:0xf bank_mask:0xf bound_ctrl:1
	v_add_f32_dpp v164, v164, v164 row_shr:2 row_mask:0xf bank_mask:0xf bound_ctrl:1
	v_add_f32_dpp v165, v165, v165 row_shr:2 row_mask:0xf bank_mask:0xf bound_ctrl:1
	v_add_f32_dpp v166, v166, v166 row_shr:2 row_mask:0xf bank_mask:0xf bound_ctrl:1
	v_add_f32_dpp v167, v167, v167 row_shr:2 row_mask:0xf bank_mask:0xf bound_ctrl:1
	v_add_f32_dpp v152, v152, v152 row_shr:4 row_mask:0xf bank_mask:0xf bound_ctrl:1
	v_add_f32_dpp v153, v153, v153 row_shr:4 row_mask:0xf bank_mask:0xf bound_ctrl:1
	v_add_f32_dpp v154, v154, v154 row_shr:4 row_mask:0xf bank_mask:0xf bound_ctrl:1
	v_add_f32_dpp v155, v155, v155 row_shr:4 row_mask:0xf bank_mask:0xf bound_ctrl:1
	v_add_f32_dpp v156, v156, v156 row_shr:4 row_mask:0xf bank_mask:0xf bound_ctrl:1
	v_add_f32_dpp v157, v157, v157 row_shr:4 row_mask:0xf bank_mask:0xf bound_ctrl:1
	v_add_f32_dpp v158, v158, v158 row_shr:4 row_mask:0xf bank_mask:0xf bound_ctrl:1
; #define LAS __attribute__((address_space(3)))
; __device__ __forceinline__ unsigned pk_bf16(float lo, float hi) { const f32x2_t f = {lo, hi}; return __builtin_bit_cast(unsigned, __builtin_convertvector(f, bf16x2_t)); }
; __device__ __forceinline__ float bf2f(bf16_t b) { return __uint_as_float(((unsigned)b) << 16); }
; __device__ __forceinline__ void phase_scan2(const Params& p, int l, LAS unsigned char* lds) {
;     ...
;               if (fr == 0) { *(LAS f32x4*)(sl + SC_X + fq * 16) = sq; *(LAS f32x4*)(sl + SC_X + 64 + fq * 16) = sb; }
;               asm volatile("s_waitcnt lgkmcnt(0)" ::: "memory");
;               if (rg == 0 && lane < 16) CB[(tok0 + (size_t)c * 16 + lane) * 8 + h] = *(LAS const float*)(sl + SC_X + 64 + lane * 4);
;               asm volatile("s_waitcnt lgkmcnt(0)" ::: "memory");
;             }
; #pragma unroll
;             for (int t = 0; t < 16; ++t) {
;                 const float k = bf2f(kraw[t]), a = bf2f(araw[t]), r = bf2f(rraw[t]), ew = (float)eraw[t];
;                 const float kk = k * kkc * rsqrtf(fmaxf(*(LAS const float*)(sl + SC_X + t * 4), 1e-24f));
;                 const float kp = k * (1.f + (a - 1.f) * kac);
;                 const float at = -kk * W;
;                 W *= __expf(-ew);
;                 const float rt = r * W, iw = __builtin_amdgcn_rcpf(W);
;                 const unsigned wbk = pk_bf16(kk * a * iw, kp * iw), war = pk_bf16(at, rt);
;                 const bf16_t bh = (bf16_t)(wbk & 0xffffu), kh = (bf16_t)(wbk >> 16), ah = (bf16_t)(war & 0xffffu), rh = (bf16_t)(war >> 16);
;                 *(LAS bf16_t*)(sl + SC_AT + ((m * 16 + t) * 32 + pidx) * 2) = ah;
;                 *(LAS bf16_t*)(sl + SC_RT + ((m * 16 + t) * 32 + pidx) * 2) = rh;
;                 *(LAS bf16_t*)(sl + SC_BBT + (j * SC_BS + t) * 2) = bh;
;                 *(LAS bf16_t*)(sl + SC_KBT + (j * SC_BS + t) * 2) = kh;
;                 *(LAS bf16_t*)(sc + 0 + ((m * 16 + t) * 32 + pidx) * 2) = bh;
;                 *(LAS bf16_t*)(sc + 2048 + ((m * 16 + t) * 32 + pidx) * 2) = kh;
;             }
	v_add_f32_dpp v159, v159, v159 row_shr:4 row_mask:0xf bank_mask:0xf bound_ctrl:1
	v_add_f32_dpp v160, v160, v160 row_shr:4 row_mask:0xf bank_mask:0xf bound_ctrl:1
	v_add_f32_dpp v161, v161, v161 row_shr:4 row_mask:0xf bank_mask:0xf bound_ctrl:1
	v_add_f32_dpp v162, v162, v162 row_shr:4 row_mask:0xf bank_mask:0xf bound_ctrl:1
	v_add_f32_dpp v163, v163, v163 row_shr:4 row_mask:0xf bank_mask:0xf bound_ctrl:1
	v_add_f32_dpp v164, v164, v164 row_shr:4 row_mask:0xf bank_mask:0xf bound_ctrl:1
	v_add_f32_dpp v165, v165, v165 row_shr:4 row_mask:0xf bank_mask:0xf bound_ctrl:1
	v_add_f32_dpp v166, v166, v166 row_shr:4 row_mask:0xf bank_mask:0xf bound_ctrl:1
	v_add_f32_dpp v167, v167, v167 row_shr:4 row_mask:0xf bank_mask:0xf bound_ctrl:1
	v_add_f32_dpp v152, v152, v152 row_shr:8 row_mask:0xf bank_mask:0xf bound_ctrl:1
	v_add_f32_dpp v153, v153, v153 row_shr:8 row_mask:0xf bank_mask:0xf bound_ctrl:1
	v_add_f32_dpp v154, v154, v154 row_shr:8 row_mask:0xf bank_mask:0xf bound_ctrl:1
	v_add_f32_dpp v155, v155, v155 row_shr:8 row_mask:0xf bank_mask:0xf bound_ctrl:1
	v_add_f32_dpp v156, v156, v156 row_shr:8 row_mask:0xf bank_mask:0xf bound_ctrl:1
	v_add_f32_dpp v157, v157, v157 row_shr:8 row_mask:0xf bank_mask:0xf bound_ctrl:1
	v_add_f32_dpp v158, v158, v158 row_shr:8 row_mask:0xf bank_mask:0xf bound_ctrl:1
	v_add_f32_dpp v159, v159, v159 row_shr:8 row_mask:0xf bank_mask:0xf bound_ctrl:1
	v_add_f32_dpp v160, v160, v160 row_shr:8 row_mask:0xf bank_mask:0xf bound_ctrl:1
	v_add_f32_dpp v161, v161, v161 row_shr:8 row_mask:0xf bank_mask:0xf bound_ctrl:1
	v_add_f32_dpp v162, v162, v162 row_shr:8 row_mask:0xf bank_mask:0xf bound_ctrl:1
	v_add_f32_dpp v163, v163, v163 row_shr:8 row_mask:0xf bank_mask:0xf bound_ctrl:1
	v_add_f32_dpp v164, v164, v164 row_shr:8 row_mask:0xf bank_mask:0xf bound_ctrl:1
	v_add_f32_dpp v165, v165, v165 row_shr:8 row_mask:0xf bank_mask:0xf bound_ctrl:1
	v_add_f32_dpp v166, v166, v166 row_shr:8 row_mask:0xf bank_mask:0xf bound_ctrl:1
	v_add_f32_dpp v167, v167, v167 row_shr:8 row_mask:0xf bank_mask:0xf bound_ctrl:1
	v_exp_f32_e32 v196, v152
	v_exp_f32_e32 v197, v153
	v_exp_f32_e32 v198, v154
	v_exp_f32_e32 v199, v155
	v_exp_f32_e32 v200, v156
	v_exp_f32_e32 v201, v157
	v_exp_f32_e32 v202, v158
	v_exp_f32_e32 v203, v159
	v_exp_f32_e32 v204, v160
	v_exp_f32_e32 v205, v161
	v_exp_f32_e32 v206, v162
	v_exp_f32_e32 v207, v163
	v_exp_f32_e32 v208, v164
	v_exp_f32_e32 v209, v165
	v_exp_f32_e32 v210, v166
	v_exp_f32_e32 v211, v167
	v_max_f32_e32 v188, 0x179abe15, v168
	v_rsq_f32_e32 v188, v188
	v_exp_f32_e64 v152, -v152
	v_exp_f32_e64 v153, -v153
	v_exp_f32_e64 v154, -v154
	v_exp_f32_e64 v155, -v155
	v_exp_f32_e64 v156, -v156
	v_exp_f32_e64 v157, -v157
	v_exp_f32_e64 v158, -v158
	v_exp_f32_e64 v159, -v159
	v_exp_f32_e64 v160, -v160
	v_exp_f32_e64 v161, -v161
	v_exp_f32_e64 v162, -v162
	v_exp_f32_e64 v163, -v163
	v_exp_f32_e64 v164, -v164
	v_exp_f32_e64 v165, -v165
	v_exp_f32_e64 v166, -v166
	v_exp_f32_e64 v167, -v167
	s_cmp_lg_u32 s53, 0
	s_nop 0
	s_cbranch_scc1 .Lsc_p_nocb
	s_mov_b64 exec, 0xffff
	global_store_dword v10, v172, s[50:51]
	s_mov_b64 exec, -1
.Lsc_p_nocb:
	v_pk_mul_f32 v[88:89], v[88:89], v[188:189] op_sel_hi:[1,0]
	v_mov_b32_dpp v76, v196 row_shr:1 row_mask:0xf bank_mask:0xf bound_ctrl:1
	v_mov_b32_dpp v77, v197 row_shr:1 row_mask:0xf bank_mask:0xf bound_ctrl:1
	v_pk_mul_f32 v[80:81], v[120:121], v[196:197]
	v_pk_mul_f32 v[104:105], v[88:89], v[104:105]
	v_max_f32_e32 v76, v76, v26
	v_max_f32_e32 v77, v77, v26
	v_pk_mul_f32 v[176:177], v[104:105], v[152:153]
	v_pk_mul_f32 v[186:187], v[136:137], v[152:153]
	v_pk_mul_f32 v[76:77], v[88:89], v[76:77] neg_lo:[1,0] neg_hi:[1,0]
	v_cvt_pk_bf16_f32 v220, v80, v81
	v_cvt_pk_bf16_f32 v228, v176, v177
	v_cvt_pk_bf16_f32 v236, v186, v187
	v_cvt_pk_bf16_f32 v168, v76, v77
	ds_write_b16 v18, v228 offset:0
	ds_write_b16_d16_hi v18, v228 offset:40
	ds_write_b16 v18, v236 offset:2560
	ds_write_b16_d16_hi v18, v236 offset:2600
	v_pk_mul_f32 v[90:91], v[90:91], v[188:189] op_sel_hi:[1,0]
	v_mov_b32_dpp v76, v198 row_shr:1 row_mask:0xf bank_mask:0xf bound_ctrl:1
	v_mov_b32_dpp v77, v199 row_shr:1 row_mask:0xf bank_mask:0xf bound_ctrl:1
	v_pk_mul_f32 v[80:81], v[122:123], v[198:199]
	v_pk_mul_f32 v[106:107], v[90:91], v[106:107]
	v_max_f32_e32 v76, v76, v26
	v_max_f32_e32 v77, v77, v26
	v_pk_mul_f32 v[176:177], v[106:107], v[154:155]
	v_pk_mul_f32 v[186:187], v[138:139], v[154:155]
	v_pk_mul_f32 v[76:77], v[90:91], v[76:77] neg_lo:[1,0] neg_hi:[1,0]
	v_cvt_pk_bf16_f32 v221, v80, v81
	v_cvt_pk_bf16_f32 v229, v176, v177
	v_cvt_pk_bf16_f32 v237, v186, v187
	v_cvt_pk_bf16_f32 v169, v76, v77
	ds_write_b16 v18, v229 offset:80
	ds_write_b16_d16_hi v18, v229 offset:120
	ds_write_b16 v18, v237 offset:2640
	ds_write_b16_d16_hi v18, v237 offset:2680
	v_pk_mul_f32 v[92:93], v[92:93], v[188:189] op_sel_hi:[1,0]
	v_mov_b32_dpp v76, v200 row_shr:1 row_mask:0xf bank_mask:0xf bound_ctrl:1
	v_mov_b32_dpp v77, v201 row_shr:1 row_mask:0xf bank_mask:0xf bound_ctrl:1
	v_pk_mul_f32 v[80:81], v[124:125], v[200:201]
	v_pk_mul_f32 v[108:109], v[92:93], v[108:109]
	v_max_f32_e32 v76, v76, v26
	v_max_f32_e32 v77, v77, v26
	v_pk_mul_f32 v[176:177], v[108:109], v[156:157]
	v_pk_mul_f32 v[186:187], v[140:141], v[156:157]
	v_pk_mul_f32 v[76:77], v[92:93], v[76:77] neg_lo:[1,0] neg_hi:[1,0]
	v_cvt_pk_bf16_f32 v222, v80, v81
	v_cvt_pk_bf16_f32 v230, v176, v177
	v_cvt_pk_bf16_f32 v238, v186, v187
	v_cvt_pk_bf16_f32 v170, v76, v77
	ds_write_b16 v18, v230 offset:160
	ds_write_b16_d16_hi v18, v230 offset:200
	ds_write_b16 v18, v238 offset:2720
	ds_write_b16_d16_hi v18, v238 offset:2760
	v_pk_mul_f32 v[94:95], v[94:95], v[188:189] op_sel_hi:[1,0]
; #define LAS __attribute__((address_space(3)))
; __device__ __forceinline__ unsigned pk_bf16(float lo, float hi) { const f32x2_t f = {lo, hi}; return __builtin_bit_cast(unsigned, __builtin_convertvector(f, bf16x2_t)); }
; __device__ __forceinline__ void phase_scan2(const Params& p, int l, LAS unsigned char* lds) {
;     ...
;                 const unsigned wbk = pk_bf16(kk * a * iw, kp * iw), war = pk_bf16(at, rt);
;                 const bf16_t bh = (bf16_t)(wbk & 0xffffu), kh = (bf16_t)(wbk >> 16), ah = (bf16_t)(war & 0xffffu), rh = (bf16_t)(war >> 16);
;                 *(LAS bf16_t*)(sl + SC_AT + ((m * 16 + t) * 32 + pidx) * 2) = ah;
;                 *(LAS bf16_t*)(sl + SC_RT + ((m * 16 + t) * 32 + pidx) * 2) = rh;
;                 *(LAS bf16_t*)(sl + SC_BBT + (j * SC_BS + t) * 2) = bh;
;                 *(LAS bf16_t*)(sl + SC_KBT + (j * SC_BS + t) * 2) = kh;
;                 *(LAS bf16_t*)(sc + 0 + ((m * 16 + t) * 32 + pidx) * 2) = bh;
;                 *(LAS bf16_t*)(sc + 2048 + ((m * 16 + t) * 32 + pidx) * 2) = kh;
;             }
;             *(LAS float*)(sl + SC_WC + j * 4) = W;
; #pragma unroll
;             for (int q = 0; q < 4; ++q) *(LAS bf16_t*)(sl + SC_VP + (fr * 16 + 4 * fq + q) * 2) = vraw[q];
;             if (cnext >= 0) pload(cnext);
;             asm volatile("s_waitcnt lgkmcnt(0)" ::: "memory");
;             f32x4 AB = (f32x4){0.f, 0.f, 0.f, 0.f}, AKm = AB, RBm = AB, RKm = AB;
; #pragma unroll
;             for (int kk2 = 0; kk2 < 2; ++kk2) {
;                 const int fo = ((kk2 * 16 + fr) * 32 + fq * 8) * 2;
;                 const bf16x8 fa = *(LAS const bf16x8*)(sl + SC_AT + fo), fr_ = *(LAS const bf16x8*)(sl + SC_RT + fo);
;                 const bf16x8 fb = *(LAS const bf16x8*)(sc + 0 + fo), fk = *(LAS const bf16x8*)(sc + 2048 + fo);
;                 AB = __builtin_amdgcn_mfma_f32_16x16x32_bf16(fa, fb, AB, 0, 0, 0); AKm = __builtin_amdgcn_mfma_f32_16x16x32_bf16(fa, fk, AKm, 0, 0, 0);
;                 RBm = __builtin_amdgcn_mfma_f32_16x16x32_bf16(fr_, fb, RBm, 0, 0, 0); RKm = __builtin_amdgcn_mfma_f32_16x16x32_bf16(fr_, fk, RKm, 0, 0, 0);
;             }
; #pragma unroll
;             for (int r = 0; r < 4; ++r) { const int t = 4 * fq + r; const bool lo = fr < t, le = fr <= t;
;                 AB[r] = lo ? AB[r] : 0.f; AKm[r] = lo ? AKm[r] : 0.f; RBm[r] = le ? RBm[r] : 0.f; RKm[r] = le ? RKm[r] : 0.f; }
	v_mov_b32_dpp v76, v202 row_shr:1 row_mask:0xf bank_mask:0xf bound_ctrl:1
	v_mov_b32_dpp v77, v203 row_shr:1 row_mask:0xf bank_mask:0xf bound_ctrl:1
	v_pk_mul_f32 v[80:81], v[126:127], v[202:203]
	v_pk_mul_f32 v[110:111], v[94:95], v[110:111]
	v_max_f32_e32 v76, v76, v26
	v_max_f32_e32 v77, v77, v26
	v_pk_mul_f32 v[176:177], v[110:111], v[158:159]
	v_pk_mul_f32 v[186:187], v[142:143], v[158:159]
	v_pk_mul_f32 v[76:77], v[94:95], v[76:77] neg_lo:[1,0] neg_hi:[1,0]
	v_cvt_pk_bf16_f32 v223, v80, v81
	v_cvt_pk_bf16_f32 v231, v176, v177
	v_cvt_pk_bf16_f32 v239, v186, v187
	v_cvt_pk_bf16_f32 v171, v76, v77
	ds_write_b16 v18, v231 offset:240
	ds_write_b16_d16_hi v18, v231 offset:280
	ds_write_b16 v18, v239 offset:2800
	ds_write_b16_d16_hi v18, v239 offset:2840
	v_pk_mul_f32 v[96:97], v[96:97], v[188:189] op_sel_hi:[1,0]
	v_mov_b32_dpp v76, v204 row_shr:1 row_mask:0xf bank_mask:0xf bound_ctrl:1
	v_mov_b32_dpp v77, v205 row_shr:1 row_mask:0xf bank_mask:0xf bound_ctrl:1
	v_pk_mul_f32 v[80:81], v[128:129], v[204:205]
	v_pk_mul_f32 v[112:113], v[96:97], v[112:113]
	v_max_f32_e32 v76, v76, v26
	v_max_f32_e32 v77, v77, v26
	v_pk_mul_f32 v[176:177], v[112:113], v[160:161]
	v_pk_mul_f32 v[186:187], v[144:145], v[160:161]
	v_pk_mul_f32 v[76:77], v[96:97], v[76:77] neg_lo:[1,0] neg_hi:[1,0]
	v_cvt_pk_bf16_f32 v224, v80, v81
	v_cvt_pk_bf16_f32 v232, v176, v177
	v_cvt_pk_bf16_f32 v244, v186, v187
	v_cvt_pk_bf16_f32 v172, v76, v77
	ds_write_b16 v18, v232 offset:320
	ds_write_b16_d16_hi v18, v232 offset:360
	ds_write_b16 v18, v244 offset:2880
	ds_write_b16_d16_hi v18, v244 offset:2920
	v_pk_mul_f32 v[98:99], v[98:99], v[188:189] op_sel_hi:[1,0]
	v_mov_b32_dpp v76, v206 row_shr:1 row_mask:0xf bank_mask:0xf bound_ctrl:1
	v_mov_b32_dpp v77, v207 row_shr:1 row_mask:0xf bank_mask:0xf bound_ctrl:1
	v_pk_mul_f32 v[80:81], v[130:131], v[206:207]
	v_pk_mul_f32 v[114:115], v[98:99], v[114:115]
	v_max_f32_e32 v76, v76, v26
	v_max_f32_e32 v77, v77, v26
	v_pk_mul_f32 v[176:177], v[114:115], v[162:163]
	v_pk_mul_f32 v[186:187], v[146:147], v[162:163]
	v_pk_mul_f32 v[76:77], v[98:99], v[76:77] neg_lo:[1,0] neg_hi:[1,0]
	v_cvt_pk_bf16_f32 v225, v80, v81
	v_cvt_pk_bf16_f32 v233, v176, v177
	v_cvt_pk_bf16_f32 v245, v186, v187
	v_cvt_pk_bf16_f32 v173, v76, v77
	ds_write_b16 v18, v233 offset:400
	ds_write_b16_d16_hi v18, v233 offset:440
	ds_write_b16 v18, v245 offset:2960
	ds_write_b16_d16_hi v18, v245 offset:3000
	v_pk_mul_f32 v[100:101], v[100:101], v[188:189] op_sel_hi:[1,0]
	v_mov_b32_dpp v76, v208 row_shr:1 row_mask:0xf bank_mask:0xf bound_ctrl:1
	v_mov_b32_dpp v77, v209 row_shr:1 row_mask:0xf bank_mask:0xf bound_ctrl:1
	v_pk_mul_f32 v[80:81], v[132:133], v[208:209]
	v_pk_mul_f32 v[116:117], v[100:101], v[116:117]
	v_max_f32_e32 v76, v76, v26
	v_max_f32_e32 v77, v77, v26
	v_pk_mul_f32 v[176:177], v[116:117], v[164:165]
	v_pk_mul_f32 v[186:187], v[148:149], v[164:165]
	v_pk_mul_f32 v[76:77], v[100:101], v[76:77] neg_lo:[1,0] neg_hi:[1,0]
	v_cvt_pk_bf16_f32 v226, v80, v81
	v_cvt_pk_bf16_f32 v234, v176, v177
	v_cvt_pk_bf16_f32 v246, v186, v187
	v_cvt_pk_bf16_f32 v174, v76, v77
	ds_write_b16 v18, v234 offset:480
	ds_write_b16_d16_hi v18, v234 offset:520
	ds_write_b16 v18, v246 offset:3040
	ds_write_b16_d16_hi v18, v246 offset:3080
	v_pk_mul_f32 v[102:103], v[102:103], v[188:189] op_sel_hi:[1,0]
	v_mov_b32_dpp v76, v210 row_shr:1 row_mask:0xf bank_mask:0xf bound_ctrl:1
	v_mov_b32_dpp v77, v211 row_shr:1 row_mask:0xf bank_mask:0xf bound_ctrl:1
	v_pk_mul_f32 v[80:81], v[134:135], v[210:211]
	v_pk_mul_f32 v[118:119], v[102:103], v[118:119]
	v_max_f32_e32 v76, v76, v26
	v_max_f32_e32 v77, v77, v26
	v_pk_mul_f32 v[176:177], v[118:119], v[166:167]
	v_pk_mul_f32 v[186:187], v[150:151], v[166:167]
	v_pk_mul_f32 v[76:77], v[102:103], v[76:77] neg_lo:[1,0] neg_hi:[1,0]
	v_cvt_pk_bf16_f32 v227, v80, v81
	v_cvt_pk_bf16_f32 v235, v176, v177
	v_cvt_pk_bf16_f32 v247, v186, v187
	v_cvt_pk_bf16_f32 v175, v76, v77
	ds_write_b16 v18, v235 offset:560
	ds_write_b16_d16_hi v18, v235 offset:600
	ds_write_b16 v18, v247 offset:3120
	ds_write_b16_d16_hi v18, v247 offset:3160
	ds_write_b64 v17, v[168:169] offset:0
	ds_write_b64 v17, v[220:221] offset:2048
	ds_write_b64 v17, v[170:171] offset:16
	ds_write_b64 v17, v[222:223] offset:2064
	ds_write_b64 v17, v[172:173] offset:32
	ds_write_b64 v17, v[224:225] offset:2080
	ds_write_b64 v17, v[174:175] offset:48
	ds_write_b64 v17, v[226:227] offset:2096
	s_mov_b32 exec_lo, 0x80008000
	s_mov_b32 exec_hi, 0x80008000
	ds_write_b128 v21, v[196:199] offset:0
	ds_write_b128 v21, v[200:203] offset:16
	ds_write_b128 v21, v[204:207] offset:32
	ds_write_b128 v21, v[208:211] offset:48
	s_mov_b64 exec, -1
	v_mfma_f32_16x16x32_bf16 v[88:91], v[168:171], v[228:231], 0
	v_mfma_f32_16x16x32_bf16 v[92:95], v[168:171], v[236:239], 0
	v_mfma_f32_16x16x32_bf16 v[96:99], v[220:223], v[228:231], 0
	v_mfma_f32_16x16x32_bf16 v[100:103], v[220:223], v[236:239], 0
	v_mfma_f32_16x16x32_bf16 v[88:91], v[172:175], v[232:235], v[88:91]
	v_mfma_f32_16x16x32_bf16 v[92:95], v[172:175], v[244:247], v[92:95]
	v_mfma_f32_16x16x32_bf16 v[96:99], v[224:227], v[232:235], v[96:99]
	v_mfma_f32_16x16x32_bf16 v[100:103], v[224:227], v[244:247], v[100:103]
	s_nop 4
	v_mul_f32_e32 v88, v35, v88
	v_mul_f32_e32 v89, v36, v89
	v_mul_f32_e32 v90, v37, v90
	v_mul_f32_e32 v91, v38, v91
	v_mul_f32_e32 v92, v35, v92
	v_mul_f32_e32 v93, v36, v93
	v_mul_f32_e32 v94, v37, v94
	v_mul_f32_e32 v95, v38, v95
	v_mul_f32_e32 v96, v39, v96
	v_mul_f32_e32 v97, v40, v97
	v_mul_f32_e32 v98, v41, v98
	v_mul_f32_e32 v99, v42, v99
	v_mul_f32_e32 v100, v39, v100
	v_mul_f32_e32 v101, v40, v101
	v_mul_f32_e32 v102, v41, v102
; __device__ __forceinline__ void st_mat(LAS unsigned char* rm, LAS unsigned char* tr, LAS unsigned char* trI, LAS unsigned char* rmI, const f32x4 c, int fr, int fq) {
; #pragma unroll
;     for (int r = 0; r < 4; ++r) { const int t = 4 * fq + r; const float v = c[r], vi = v + (t == fr ? 1.f : 0.f);
;         if (rm) *(LAS bf16_t*)(rm + (t * 16 + fr) * 2) = bf1(v);
;         if (tr) *(LAS bf16_t*)(tr + (fr * 16 + t) * 2) = bf1(v);
;         if (trI) *(LAS bf16_t*)(trI + (fr * 16 + t) * 2) = bf1(vi);
;         if (rmI) *(LAS bf16_t*)(rmI + (t * 16 + fr) * 2) = bf1(vi); }
; }
; __device__ __forceinline__ f32x4 mm16(LAS const unsigned char* Arm, LAS const unsigned char* Btr, int fr, int fq) {
;     asm volatile("s_waitcnt lgkmcnt(0)" ::: "memory");
;     const bf16x8 a = frag4(Arm + (fr * 16 + 4 * fq) * 2), b = frag4(Btr + (fr * 16 + 4 * fq) * 2);
;     return __builtin_amdgcn_mfma_f32_16x16x32_bf16(a, b, (f32x4){0.f, 0.f, 0.f, 0.f}, 0, 0, 0);
; }
; __device__ __forceinline__ void phase_scan2(const Params& p, int l, LAS unsigned char* lds) {
;     ...
;             asm volatile("s_waitcnt lgkmcnt(0)" ::: "memory");
;             st_mat(sl + SC_AK, nullptr, nullptr, nullptr, AKm, fr, fq);
;             st_mat(sl + SC_RB, nullptr, nullptr, nullptr, RBm, fr, fq);
;             st_mat(sl + SC_RK, nullptr, nullptr, nullptr, RKm, fr, fq);
;             LAS unsigned char* mL = sc, *mLT = sc + 512, *mIL = sc + 1024, *mL2 = sc + 1536, *mL2T = sc + 2048, *mIL2T = sc + 2560, *mL4 = sc + 3072, *mL4T = sc + 3584, *mIL4T = sc + 4096, *mIL8T = sc + 4608, *mP1 = sc + 5120, *mP2 = sc + 5632;
;             st_mat(mL, mLT, nullptr, mIL, AB, fr, fq);
;             const f32x4 L2 = mm16(mL, mLT, fr, fq);      st_mat(mL2, mL2T, mIL2T, nullptr, L2, fr, fq);
;             const f32x4 L4 = mm16(mL2, mL2T, fr, fq);    const f32x4 P1 = mm16(mIL, mIL2T, fr, fq);
;             st_mat(mL4, mL4T, mIL4T, nullptr, L4, fr, fq); st_mat(mP1, nullptr, nullptr, nullptr, P1, fr, fq);
;             const f32x4 L8 = mm16(mL4, mL4T, fr, fq);    const f32x4 P2 = mm16(mP1, mIL4T, fr, fq);
;             st_mat(nullptr, nullptr, mIL8T, nullptr, L8, fr, fq); st_mat(mP2, nullptr, nullptr, nullptr, P2, fr, fq);
;             const f32x4 X = mm16(mP2, mIL8T, fr, fq);    st_mat(sl + SC_X, nullptr, nullptr, nullptr, X, fr, fq);
;             asm volatile("s_waitcnt lgkmcnt(0)" ::: "memory");
	v_mul_f32_e32 v103, v42, v103
	v_cvt_pk_bf16_f32 v76, v92, v92
	ds_write_b16 v20, v76 offset:9216
	v_cvt_pk_bf16_f32 v76, v93, v93
	ds_write_b16 v20, v76 offset:9248
	v_cvt_pk_bf16_f32 v76, v94, v94
	ds_write_b16 v20, v76 offset:9280
	v_cvt_pk_bf16_f32 v76, v95, v95
	ds_write_b16 v20, v76 offset:9312
	v_cvt_pk_bf16_f32 v76, v96, v96
	ds_write_b16 v20, v76 offset:10240
	v_cvt_pk_bf16_f32 v76, v97, v97
	ds_write_b16 v20, v76 offset:10272
	v_cvt_pk_bf16_f32 v76, v98, v98
	ds_write_b16 v20, v76 offset:10304
	v_cvt_pk_bf16_f32 v76, v99, v99
	ds_write_b16 v20, v76 offset:10336
	v_cvt_pk_bf16_f32 v76, v100, v100
	ds_write_b16 v20, v76 offset:10752
	v_cvt_pk_bf16_f32 v76, v101, v101
	ds_write_b16 v20, v76 offset:10784
	v_cvt_pk_bf16_f32 v76, v102, v102
	ds_write_b16 v20, v76 offset:10816
	v_cvt_pk_bf16_f32 v76, v103, v103
	ds_write_b16 v20, v76 offset:10848
	v_add_f32_e32 v80, v27, v88
	v_cvt_pk_bf16_f32 v76, v88, v88
	v_cvt_pk_bf16_f32 v77, v80, v80
	ds_write_b16 v14, v76 offset:0
	ds_write_b16 v15, v76 offset:512
	ds_write_b16 v14, v77 offset:1024
	v_add_f32_e32 v80, v32, v89
	v_cvt_pk_bf16_f32 v76, v89, v89
	v_cvt_pk_bf16_f32 v77, v80, v80
	ds_write_b16 v14, v76 offset:32
	ds_write_b16 v15, v76 offset:514
	ds_write_b16 v14, v77 offset:1056
	v_add_f32_e32 v80, v33, v90
	v_cvt_pk_bf16_f32 v76, v90, v90
	v_cvt_pk_bf16_f32 v77, v80, v80
	ds_write_b16 v14, v76 offset:64
	ds_write_b16 v15, v76 offset:516
	ds_write_b16 v14, v77 offset:1088
	v_add_f32_e32 v80, v34, v91
	v_cvt_pk_bf16_f32 v76, v91, v91
	v_cvt_pk_bf16_f32 v77, v80, v80
	ds_write_b16 v14, v76 offset:96
	ds_write_b16 v15, v76 offset:518
	ds_write_b16 v14, v77 offset:1120
	s_waitcnt lgkmcnt(0)
	ds_read_b64 v[112:113], v15 offset:0
	ds_read_b64 v[114:115], v15 offset:512
	s_waitcnt lgkmcnt(0)
	v_mfma_f32_16x16x16_bf16 v[104:107], v[112:113], v[114:115], 0
	s_nop 7
	v_add_f32_e32 v80, v27, v104
	v_cvt_pk_bf16_f32 v76, v104, v104
	v_cvt_pk_bf16_f32 v77, v80, v80
	ds_write_b16 v14, v76 offset:1536
	ds_write_b16 v15, v76 offset:2048
	ds_write_b16 v15, v77 offset:2560
	v_add_f32_e32 v80, v32, v105
	v_cvt_pk_bf16_f32 v76, v105, v105
	v_cvt_pk_bf16_f32 v77, v80, v80
	ds_write_b16 v14, v76 offset:1568
	ds_write_b16 v15, v76 offset:2050
	ds_write_b16 v15, v77 offset:2562
	v_add_f32_e32 v80, v33, v106
	v_cvt_pk_bf16_f32 v76, v106, v106
	v_cvt_pk_bf16_f32 v77, v80, v80
	ds_write_b16 v14, v76 offset:1600
	ds_write_b16 v15, v76 offset:2052
	ds_write_b16 v15, v77 offset:2564
	v_add_f32_e32 v80, v34, v107
	v_cvt_pk_bf16_f32 v76, v107, v107
	v_cvt_pk_bf16_f32 v77, v80, v80
	ds_write_b16 v14, v76 offset:1632
	ds_write_b16 v15, v76 offset:2054
	ds_write_b16 v15, v77 offset:2566
	s_waitcnt lgkmcnt(0)
	ds_read_b64 v[112:113], v15 offset:1536
	ds_read_b64 v[114:115], v15 offset:2048
	ds_read_b64 v[116:117], v15 offset:1024
	ds_read_b64 v[118:119], v15 offset:2560
	s_waitcnt lgkmcnt(2)
	v_mfma_f32_16x16x16_bf16 v[104:107], v[112:113], v[114:115], 0
	s_waitcnt lgkmcnt(0)
	v_mfma_f32_16x16x16_bf16 v[108:111], v[116:117], v[118:119], 0
	s_nop 5
	v_add_f32_e32 v80, v27, v104
	v_cvt_pk_bf16_f32 v76, v104, v104
	v_cvt_pk_bf16_f32 v77, v80, v80
	ds_write_b16 v14, v76 offset:3072
	ds_write_b16 v15, v76 offset:3584
	ds_write_b16 v15, v77 offset:4096
	v_add_f32_e32 v80, v32, v105
	v_cvt_pk_bf16_f32 v76, v105, v105
	v_cvt_pk_bf16_f32 v77, v80, v80
	ds_write_b16 v14, v76 offset:3104
	ds_write_b16 v15, v76 offset:3586
	ds_write_b16 v15, v77 offset:4098
	v_add_f32_e32 v80, v33, v106
	v_cvt_pk_bf16_f32 v76, v106, v106
	v_cvt_pk_bf16_f32 v77, v80, v80
	ds_write_b16 v14, v76 offset:3136
	ds_write_b16 v15, v76 offset:3588
	ds_write_b16 v15, v77 offset:4100
	v_add_f32_e32 v80, v34, v107
	v_cvt_pk_bf16_f32 v76, v107, v107
	v_cvt_pk_bf16_f32 v77, v80, v80
	ds_write_b16 v14, v76 offset:3168
	ds_write_b16 v15, v76 offset:3590
	ds_write_b16 v15, v77 offset:4102
	v_cvt_pk_bf16_f32 v76, v108, v108
	ds_write_b16 v14, v76 offset:4608
	v_cvt_pk_bf16_f32 v76, v109, v109
	ds_write_b16 v14, v76 offset:4640
	v_cvt_pk_bf16_f32 v76, v110, v110
	ds_write_b16 v14, v76 offset:4672
	v_cvt_pk_bf16_f32 v76, v111, v111
	ds_write_b16 v14, v76 offset:4704
	s_waitcnt lgkmcnt(0)
	ds_read_b64 v[112:113], v15 offset:3072
	ds_read_b64 v[114:115], v15 offset:3584
	ds_read_b64 v[116:117], v15 offset:4608
	ds_read_b64 v[118:119], v15 offset:4096
	s_waitcnt lgkmcnt(2)
	v_mfma_f32_16x16x16_bf16 v[104:107], v[112:113], v[114:115], 0
	s_waitcnt lgkmcnt(0)
	v_mfma_f32_16x16x16_bf16 v[108:111], v[116:117], v[118:119], 0
	s_nop 5
	v_add_f32_e32 v80, v27, v104
	v_cvt_pk_bf16_f32 v76, v104, v104
	v_cvt_pk_bf16_f32 v77, v80, v80
	ds_write_b16 v15, v77 offset:512
	v_add_f32_e32 v80, v32, v105
	v_cvt_pk_bf16_f32 v76, v105, v105
	v_cvt_pk_bf16_f32 v77, v80, v80
	ds_write_b16 v15, v77 offset:514
	v_add_f32_e32 v80, v33, v106
	v_cvt_pk_bf16_f32 v76, v106, v106
	v_cvt_pk_bf16_f32 v77, v80, v80
	ds_write_b16 v15, v77 offset:516
	v_add_f32_e32 v80, v34, v107
	v_cvt_pk_bf16_f32 v76, v107, v107
	v_cvt_pk_bf16_f32 v77, v80, v80
	ds_write_b16 v15, v77 offset:518
	v_cvt_pk_bf16_f32 v76, v108, v108
	ds_write_b16 v14, v76 offset:0
	v_cvt_pk_bf16_f32 v76, v109, v109
	ds_write_b16 v14, v76 offset:32
	v_cvt_pk_bf16_f32 v76, v110, v110
	ds_write_b16 v14, v76 offset:64
	v_cvt_pk_bf16_f32 v76, v111, v111
	ds_write_b16 v14, v76 offset:96
	s_waitcnt lgkmcnt(0)
	ds_read_b64 v[112:113], v15 offset:0
	ds_read_b64 v[114:115], v15 offset:512
	s_waitcnt lgkmcnt(0)
	v_mfma_f32_16x16x16_bf16 v[104:107], v[112:113], v[114:115], 0
	s_nop 7
	v_cvt_pk_bf16_f32 v76, v104, v104
	ds_write_b16 v20, v76 offset:9728
	v_cvt_pk_bf16_f32 v76, v105, v105
	ds_write_b16 v20, v76 offset:9760
	v_cvt_pk_bf16_f32 v76, v106, v106
	ds_write_b16 v20, v76 offset:9792
	v_cvt_pk_bf16_f32 v76, v107, v107
	ds_write_b16 v20, v76 offset:9824
	s_nop 0
; __device__ __forceinline__ void phase_scan2(const Params& p, int l, LAS unsigned char* lds) {
;     ...
;         auto consume = [&](int c, LAS const unsigned char* sl) {
;             const bf16x8 s0 = __builtin_bit_cast(bf16x8, (u32x4){pk_bf16(ST[0][0], ST[0][1]), pk_bf16(ST[0][2], ST[0][3]), pk_bf16(ST[1][0], ST[1][1]), pk_bf16(ST[1][2], ST[1][3])});
;             const bf16x8 s1 = __builtin_bit_cast(bf16x8, (u32x4){pk_bf16(ST[2][0], ST[2][1]), pk_bf16(ST[2][2], ST[2][3]), pk_bf16(ST[3][0], ST[3][1]), pk_bf16(ST[3][2], ST[3][3])});
;             const bf16x8 at0 = *(LAS const bf16x8*)(sl + SC_AT + (fr * 32 + fq * 8) * 2), at1 = *(LAS const bf16x8*)(sl + SC_AT + ((16 + fr) * 32 + fq * 8) * 2);
;             const bf16x8 rt0 = *(LAS const bf16x8*)(sl + SC_RT + (fr * 32 + fq * 8) * 2), rt1 = *(LAS const bf16x8*)(sl + SC_RT + ((16 + fr) * 32 + fq * 8) * 2);
;             const int mo = (fr * 16 + 4 * fq) * 2;
;             const bf16x8 vf = frag4(sl + SC_VP + mo), akf = frag4(sl + SC_AK + mo), xf = frag4(sl + SC_X + mo), rbf = frag4(sl + SC_RB + mo), rkf = frag4(sl + SC_RK + mo);
;             const f32x4 z = (f32x4){0.f, 0.f, 0.f, 0.f};
;             f32x4 g = __builtin_amdgcn_mfma_f32_16x16x32_bf16(at0, s0, z, 0, 0, 0);
;             g = __builtin_amdgcn_mfma_f32_16x16x32_bf16(at1, s1, g, 0, 0, 0);
;             g = __builtin_amdgcn_mfma_f32_16x16x32_bf16(akf, vf, g, 0, 0, 0);
;             const f32x4 sa = __builtin_amdgcn_mfma_f32_16x16x32_bf16(xf, cfrag(g), z, 0, 0, 0);
;             const bf16x8 saf = cfrag(sa);
;             f32x4 y = __builtin_amdgcn_mfma_f32_16x16x32_bf16(rt0, s0, z, 0, 0, 0);
;             y = __builtin_amdgcn_mfma_f32_16x16x32_bf16(rt1, s1, y, 0, 0, 0);
;             y = __builtin_amdgcn_mfma_f32_16x16x32_bf16(rbf, saf, y, 0, 0, 0);
;             y = __builtin_amdgcn_mfma_f32_16x16x32_bf16(rkf, vf, y, 0, 0, 0);
; #pragma unroll
;             for (int jt = 0; jt < 4; ++jt) {
;                 const f32x4 wc = *(LAS const f32x4*)(sl + SC_WC + (16 * jt + 4 * fq) * 4);
;                 const bf16x8 bb = frag4(sl + SC_BBT + ((16 * jt + fr) * SC_BS + 4 * fq) * 2), kb = frag4(sl + SC_KBT + ((16 * jt + fr) * SC_BS + 4 * fq) * 2);
;                 f32x4 acc = ST[jt];
;                 acc = __builtin_amdgcn_mfma_f32_16x16x32_bf16(bb, saf, acc, 0, 0, 0);
;                 acc = __builtin_amdgcn_mfma_f32_16x16x32_bf16(kb, vf, acc, 0, 0, 0);
.Lsc_p_skip:
	s_add_u32 s58, s58, 5
	s_sub_u32 s56, 61440, s56
	s_add_u32 s50, s50, 2560
	s_addc_u32 s51, s51, 0
	s_add_u32 s42, s42, 1
	s_waitcnt lgkmcnt(0)
	s_barrier
	s_cmp_le_u32 s42, 52
	s_cbranch_scc1 .Lsc_p_loop
	s_branch .Lsc_job_end
.Lsc_consumer:
	v_mov_b32_e32 v8, 0
	v_mov_b32_e32 v9, 0
	v_mov_b32_e32 v10, 0
	v_mov_b32_e32 v11, 0
	v_mov_b32_e32 v16, 0
	v_mov_b32_e32 v17, 0
	v_mov_b32_e32 v18, 0
	v_mov_b32_e32 v19, 0
	v_mov_b32_e32 v20, 0
	v_mov_b32_e32 v21, 0
	v_mov_b32_e32 v22, 0
	v_mov_b32_e32 v23, 0
	v_mov_b32_e32 v24, 0
	v_mov_b32_e32 v25, 0
	v_mov_b32_e32 v26, 0
	v_mov_b32_e32 v27, 0
	v_lshlrev_b32_e32 v113, 6, v1
	v_lshl_add_u32 v113, v2, 4, v113
	v_lshlrev_b32_e32 v114, 4, v2
	v_add_u32_e32 v114, 11776, v114
	v_mul_u32_u24_e32 v115, 40, v1
	v_lshl_add_u32 v115, v2, 3, v115
	v_add_u32_e32 v115, 4096, v115
	v_lshlrev_b32_e32 v116, 12, v2
	v_lshl_add_u32 v116, v1, 1, v116
	s_mul_i32 s0, s54, 4096
	s_lshl_b32 s0, s0, 10
	s_lshl_b32 s14, s52, 7
	s_lshl_b32 s15, s53, 5
	s_add_u32 s0, s0, s14
	s_add_u32 s0, s0, s15
	s_add_u32 s0, s0, 0x5000000
	s_add_u32 s48, s74, s0
	s_addc_u32 s49, s75, 0
	s_mov_b32 s42, 0
	s_mov_b32 s58, 0
	s_mov_b32 s56, 0
	s_branch .Lsc_c_bar
.Lsc_c_loop:
	s_mov_b32 s59, 0
	s_mov_b32 s57, s56
.Lsc_c_chunk:
	s_cmp_ge_u32 s58, 256
	s_cbranch_scc1 .Lsc_c_next
	v_add_u32_e32 v13, s57, v113
	v_add_u32_e32 v78, s57, v6
	v_add_u32_e32 v82, s57, v114
	v_add_u32_e32 v112, s57, v115
	ds_read_b128 v[36:39], v13 offset:0
	ds_read_b128 v[44:47], v13 offset:2048
	ds_read_b128 v[40:43], v13 offset:1024
	ds_read_b128 v[48:51], v13 offset:3072
	ds_read_b64 v[14:15], v78 offset:11264
	ds_read_b64 v[88:89], v112 offset:2560
	ds_read_b64 v[90:91], v112 offset:3200
	ds_read_b64 v[92:93], v112 offset:3840
	ds_read_b64 v[94:95], v112 offset:4480
	ds_read_b64 v[52:53], v78 offset:9216
	ds_read_b64 v[58:59], v78 offset:10752
	ds_read_b64 v[54:55], v78 offset:9728
	ds_read_b64 v[56:57], v78 offset:10240
	v_cvt_pk_bf16_f32 v28, v8, v9
	v_cvt_pk_bf16_f32 v29, v10, v11
	v_cvt_pk_bf16_f32 v30, v16, v17
	v_cvt_pk_bf16_f32 v31, v18, v19
	v_cvt_pk_bf16_f32 v32, v20, v21
	v_cvt_pk_bf16_f32 v33, v22, v23
	v_cvt_pk_bf16_f32 v34, v24, v25
	v_cvt_pk_bf16_f32 v35, v26, v27
	s_waitcnt lgkmcnt(12)
	v_mfma_f32_16x16x32_bf16 v[96:99], v[36:39], v[28:31], 0
	s_waitcnt lgkmcnt(11)
	v_mfma_f32_16x16x32_bf16 v[104:107], v[44:47], v[28:31], 0
	ds_read_b64 v[76:77], v112 offset:0
	ds_read_b64 v[80:81], v112 offset:640
	ds_read_b64 v[84:85], v112 offset:1280
	ds_read_b64 v[86:87], v112 offset:1920
	s_waitcnt lgkmcnt(14)
	v_mfma_f32_16x16x32_bf16 v[96:99], v[40:43], v[32:35], v[96:99]
	s_waitcnt lgkmcnt(13)
	v_mfma_f32_16x16x32_bf16 v[104:107], v[48:51], v[32:35], v[104:107]
	s_waitcnt lgkmcnt(8)
	v_mfma_f32_16x16x16_bf16 v[8:11], v[88:89], v[14:15], v[8:11]
	v_mfma_f32_16x16x16_bf16 v[16:19], v[90:91], v[14:15], v[16:19]
	v_mfma_f32_16x16x16_bf16 v[20:23], v[92:93], v[14:15], v[20:23]
	v_mfma_f32_16x16x16_bf16 v[24:27], v[94:95], v[14:15], v[24:27]
	ds_read_b128 v[60:63], v82 offset:0
	ds_read_b128 v[64:67], v82 offset:64
	ds_read_b128 v[68:71], v82 offset:128
	ds_read_b128 v[72:75], v82 offset:192
	s_waitcnt lgkmcnt(10)
	v_mfma_f32_16x16x16_bf16 v[96:99], v[52:53], v[14:15], v[96:99]
	v_mfma_f32_16x16x16_bf16 v[104:107], v[58:59], v[14:15], v[104:107]
	s_nop 6
	v_cvt_pk_bf16_f32 v108, v96, v97
	v_cvt_pk_bf16_f32 v109, v98, v99
	s_waitcnt lgkmcnt(9)
	s_nop 0
	v_mfma_f32_16x16x16_bf16 v[100:103], v[54:55], v[108:109], 0
	s_nop 7
	v_cvt_pk_bf16_f32 v110, v100, v101
	v_cvt_pk_bf16_f32 v111, v102, v103
	s_waitcnt lgkmcnt(4)
	s_nop 0
	v_mfma_f32_16x16x16_bf16 v[104:107], v[56:57], v[110:111], v[104:107]
	v_mfma_f32_16x16x16_bf16 v[8:11], v[76:77], v[110:111], v[8:11]
	v_mfma_f32_16x16x16_bf16 v[16:19], v[80:81], v[110:111], v[16:19]
	v_mfma_f32_16x16x16_bf16 v[20:23], v[84:85], v[110:111], v[20:23]
	v_mfma_f32_16x16x16_bf16 v[24:27], v[86:87], v[110:111], v[24:27]
	s_nop 3
	v_cvt_pk_bf16_f32 v117, v104, v104
	global_store_short v116, v117, s[48:49] offset:0
	v_cvt_pk_bf16_f32 v117, v105, v105
	global_store_short v116, v117, s[48:49] offset:1024
	v_cvt_pk_bf16_f32 v117, v106, v106
	global_store_short v116, v117, s[48:49] offset:2048
	v_cvt_pk_bf16_f32 v117, v107, v107
	global_store_short v116, v117, s[48:49] offset:3072
	s_waitcnt lgkmcnt(0)
	v_pk_mul_f32 v[8:9], v[8:9], v[60:61]
	v_pk_mul_f32 v[10:11], v[10:11], v[62:63]
	v_pk_mul_f32 v[16:17], v[16:17], v[64:65]
	v_pk_mul_f32 v[18:19], v[18:19], v[66:67]
	v_pk_mul_f32 v[20:21], v[20:21], v[68:69]
	v_pk_mul_f32 v[22:23], v[22:23], v[70:71]
	v_pk_mul_f32 v[24:25], v[24:25], v[72:73]
	v_pk_mul_f32 v[26:27], v[26:27], v[74:75]
	s_nop 1
.Lsc_c_next:
	s_add_u32 s58, s58, 1
	s_add_u32 s48, s48, 0x4000
	s_addc_u32 s49, s49, 0
	s_add_u32 s57, s57, 12288
	s_add_u32 s59, s59, 1
	s_cmp_lt_u32 s59, 5
	s_cbranch_scc1 .Lsc_c_chunk
	s_sub_u32 s56, 61440, s56
.Lsc_c_bar:
	s_add_u32 s42, s42, 1
	s_waitcnt lgkmcnt(0)
	s_barrier
	s_cmp_le_u32 s42, 52
	s_cbranch_scc1 .Lsc_c_loop
	s_branch .Lsc_job_end
.Lsc_idle:
	s_mov_b32 s42, 0
.Lsc_i_loop:
	s_add_u32 s42, s42, 1
	s_barrier
	s_cmp_le_u32 s42, 52
	s_cbranch_scc1 .Lsc_i_loop
.Lsc_job_end:
	s_add_u32 s13, s13, s62
	s_cmp_lt_u32 s13, 256
	s_cbranch_scc1 .Lsc_job
	s_waitcnt vmcnt(0) lgkmcnt(0)
.Lsc_exit:
.LBB0_756:
	v_readlane_b32 s56, v243, 35
	v_readlane_b32 s58, v243, 37
	v_readlane_b32 s52, v243, 41
	v_readlane_b32 s0, v243, 32
	v_readlane_b32 s80, v252, 4
	v_readlane_b32 s57, v243, 36
	v_readlane_b32 s59, v243, 38
	v_readlane_b32 s53, v243, 42
	v_readlane_b32 s81, v252, 5
	v_readlane_b32 s82, v252, 6
	v_readlane_b32 s83, v252, 7
	v_readlane_b32 s84, v252, 8
	v_readlane_b32 s85, v252, 9
	v_readlane_b32 s86, v252, 10
	v_readlane_b32 s87, v252, 11
	v_readlane_b32 s88, v252, 12
	v_readlane_b32 s89, v252, 13
	v_readlane_b32 s90, v252, 14
	v_readlane_b32 s91, v252, 15
	v_readlane_b32 s92, v252, 16
	v_readlane_b32 s93, v252, 17
	v_readlane_b32 s94, v252, 18
	v_readlane_b32 s95, v252, 19

; __global__ void __launch_bounds__(512, 2) fwd_kernel(Params p) {
	.amdhsa_kernel _Z10fwd_kernel6Params
		.amdhsa_group_segment_fixed_size 0
		.amdhsa_private_segment_fixed_size 0
		.amdhsa_kernarg_size 480
		.amdhsa_user_sgpr_count 2
		.amdhsa_user_sgpr_dispatch_ptr 0
		.amdhsa_user_sgpr_queue_ptr 0
		.amdhsa_user_sgpr_kernarg_segment_ptr 1
		.amdhsa_user_sgpr_dispatch_id 0
		.amdhsa_user_sgpr_kernarg_preload_length 0
		.amdhsa_user_sgpr_kernarg_preload_offset 0
		.amdhsa_user_sgpr_private_segment_size 0
		.amdhsa_uses_dynamic_stack 0
		.amdhsa_enable_private_segment 0
		.amdhsa_system_sgpr_workgroup_id_x 1
		.amdhsa_system_sgpr_workgroup_id_y 0
		.amdhsa_system_sgpr_workgroup_id_z 0
		.amdhsa_system_sgpr_workgroup_info 0
		.amdhsa_system_vgpr_workitem_id 2
		.amdhsa_next_free_vgpr 255
		.amdhsa_next_free_sgpr 102
		.amdhsa_accum_offset 256
		.amdhsa_reserve_vcc 1
		.amdhsa_float_round_mode_32 0
		.amdhsa_float_round_mode_16_64 0
		.amdhsa_float_denorm_mode_32 3
		.amdhsa_float_denorm_mode_16_64 3
		.amdhsa_dx10_clamp 1
		.amdhsa_ieee_mode 1
		.amdhsa_fp16_overflow 0
		.amdhsa_tg_split 0
		.amdhsa_exception_fp_ieee_invalid_op 0
		.amdhsa_exception_fp_denorm_src 0
		.amdhsa_exception_fp_ieee_div_zero 0
		.amdhsa_exception_fp_ieee_overflow 0
		.amdhsa_exception_fp_ieee_underflow 0
		.amdhsa_exception_fp_ieee_inexact 0
		.amdhsa_exception_int_div_zero 0
	.end_amdhsa_kernel

; __global__ void __launch_bounds__(512, 2) fwd_kernel(Params p) {
amdhsa.kernels:
  - .agpr_count:     0
    .args:
      - .offset:         0
        .size:           224
        .value_kind:     by_value
      - .offset:         224
        .size:           4
        .value_kind:     hidden_block_count_x
      - .offset:         228
        .size:           4
        .value_kind:     hidden_block_count_y
      - .offset:         232
        .size:           4
        .value_kind:     hidden_block_count_z
      - .offset:         236
        .size:           2
        .value_kind:     hidden_group_size_x
      - .offset:         238
        .size:           2
        .value_kind:     hidden_group_size_y
      - .offset:         240
        .size:           2
        .value_kind:     hidden_group_size_z
      - .offset:         242
        .size:           2
        .value_kind:     hidden_remainder_x
      - .offset:         244
        .size:           2
        .value_kind:     hidden_remainder_y
      - .offset:         246
        .size:           2
        .value_kind:     hidden_remainder_z
      - .offset:         264
        .size:           8
        .value_kind:     hidden_global_offset_x
      - .offset:         272
        .size:           8
        .value_kind:     hidden_global_offset_y
      - .offset:         280
        .size:           8
        .value_kind:     hidden_global_offset_z
      - .offset:         288
        .size:           2
        .value_kind:     hidden_grid_dims
      - .offset:         312
        .size:           8
        .value_kind:     hidden_multigrid_sync_arg
      - .offset:         344
        .size:           4
        .value_kind:     hidden_dynamic_lds_size
    .group_segment_fixed_size: 0
    .kernarg_segment_align: 8
    .kernarg_segment_size: 480
    .language:       OpenCL C
    .language_version:
      - 2
      - 0
    .max_flat_workgroup_size: 512
    .name:           _Z10fwd_kernel6Params
    .private_segment_fixed_size: 0
    .sgpr_count:     108
    .sgpr_spill_count: 247
    .symbol:         _Z10fwd_kernel6Params.kd
    .uniform_work_group_size: 1
    .uses_dynamic_stack: false
    .vgpr_count:     255
    .vgpr_spill_count: 0
    .wavefront_size: 64
